# v33: ssd_out D-skip scalar load hoisted to loop top, counted waits keep z prefetch in flight
# baseline (speedup 1.0000x reference)
.LBB0_1346:
	v_readlane_b32 s36, v254, 63
	v_readlane_b32 s50, v255, 13
	v_readlane_b32 s51, v255, 14
	v_readlane_b32 s37, v255, 0
	v_readlane_b32 s38, v255, 1
	v_lshl_add_u64 v[66:67], s[70:71], 2, v[130:131]
	global_load_dword v84, v[66:67], off
	global_load_dword v85, v[66:67], off offset:64
	global_load_dword v82, v[66:67], off offset:128
	global_load_dword v83, v[66:67], off offset:192
	global_load_dword v238, v99, s[54:55]
	v_lshl_add_u64 v[70:71], s[50:51], 0, v[144:145]
	v_lshl_add_u64 v[70:71], v[70:71], 0, s[76:77]
	v_add_co_u32_e32 v66, vcc, 0x8c01000, v70
	v_readlane_b32 s39, v255, 2
	s_nop 0
	v_addc_co_u32_e32 v67, vcc, 0, v71, vcc
	v_add_co_u32_e32 v70, vcc, 0x8c18000, v70
	global_load_dwordx4 v[226:229], v[66:67], off offset:2048
	s_nop 0
	v_addc_co_u32_e32 v71, vcc, 0, v71, vcc
	global_load_dwordx4 v[230:233], v[70:71], off offset:2048
	s_and_b64 vcc, exec, s[6:7]
	v_readlane_b32 s40, v255, 3
	v_readlane_b32 s41, v255, 4
	v_readlane_b32 s42, v255, 5
	v_readlane_b32 s43, v255, 6
	v_readlane_b32 s44, v255, 7
	v_readlane_b32 s45, v255, 8
	v_readlane_b32 s46, v255, 9
	v_readlane_b32 s47, v255, 10
	v_readlane_b32 s48, v255, 11
	v_readlane_b32 s49, v255, 12
	v_add_u32_e32 v66, s33, v115
	v_add_u32_e32 v67, 0x1dc00, v66
	s_waitcnt lgkmcnt(0)
	s_barrier
	ds_read_b32 v152, v67
	v_add_u32_e32 v67, 0x1dc20, v66
	ds_read_b32 v153, v67
	v_add_u32_e32 v67, 0x1dc40, v66
	v_add_u32_e32 v66, 0x1dc60, v66
	ds_read_b32 v121, v67
	ds_read_b32 v119, v66
	v_add_u32_e32 v66, s33, v175
	v_add_u32_e32 v67, 0x1dc00, v66
	ds_read_b32 v67, v67
	s_waitcnt lgkmcnt(0)
	v_sub_f32_e32 v68, v152, v67
	v_mul_f32_e32 v68, 0x3fb8aa3b, v68
	v_exp_f32_e32 v68, v68
	s_nop 0
	v_mul_f32_e32 v68, v30, v68
	v_cvt_pk_bf16_f32 v68, v68, s0
	v_cndmask_b32_e64 v68, v68, 0, s[0:1]
	ds_write_b16 v181, v68
	v_sub_f32_e32 v68, v153, v67
	v_mul_f32_e32 v68, 0x3fb8aa3b, v68
	v_exp_f32_e32 v68, v68
	s_nop 0
	v_mul_f32_e32 v68, v31, v68
	v_cvt_pk_bf16_f32 v68, v68, s0
	v_cndmask_b32_e64 v68, v68, 0, s[18:19]
	ds_write_b16 v181, v68 offset:272
	v_sub_f32_e32 v68, v121, v67
	v_sub_f32_e32 v67, v119, v67
	v_mul_f32_e32 v67, 0x3fb8aa3b, v67
	v_exp_f32_e32 v67, v67
	v_mul_f32_e32 v68, 0x3fb8aa3b, v68
	v_exp_f32_e32 v68, v68
	v_mul_f32_e32 v67, v33, v67
	v_cvt_pk_bf16_f32 v67, v67, s0
	v_cndmask_b32_e64 v67, v67, 0, s[22:23]
	ds_write_b16 v181, v67 offset:816
	v_add_u32_e32 v67, 0x1de00, v66
	ds_read_b32 v67, v67
	v_mul_f32_e32 v68, v32, v68
	v_cvt_pk_bf16_f32 v68, v68, s0
	v_cndmask_b32_e64 v68, v68, 0, s[20:21]
	ds_write_b16 v181, v68 offset:544
	s_waitcnt lgkmcnt(1)
	v_sub_f32_e32 v68, v152, v67
	v_mul_f32_e32 v68, 0x3fb8aa3b, v68
	v_exp_f32_e32 v68, v68
	s_nop 0
	v_mul_f32_e32 v68, v2, v68
	v_cvt_pk_bf16_f32 v68, v68, s0
	v_cndmask_b32_e64 v68, v68, 0, s[82:83]
	ds_write_b16 v181, v68 offset:32
	v_sub_f32_e32 v68, v153, v67
	v_mul_f32_e32 v68, 0x3fb8aa3b, v68
	v_exp_f32_e32 v68, v68
	s_nop 0
	v_mul_f32_e32 v68, v3, v68
	v_cvt_pk_bf16_f32 v68, v68, s0
	v_cndmask_b32_e64 v68, v68, 0, s[86:87]
	ds_write_b16 v181, v68 offset:304
	v_sub_f32_e32 v68, v121, v67
	v_sub_f32_e32 v67, v119, v67
	v_mul_f32_e32 v68, 0x3fb8aa3b, v68
	v_mul_f32_e32 v67, 0x3fb8aa3b, v67
	v_exp_f32_e32 v68, v68
	v_exp_f32_e32 v67, v67
	v_mul_f32_e32 v68, v4, v68
	v_mul_f32_e32 v67, v5, v67
	v_cvt_pk_bf16_f32 v68, v68, s0
	v_cvt_pk_bf16_f32 v67, v67, s0
	v_cndmask_b32_e64 v68, v68, 0, s[88:89]
	v_cndmask_b32_e64 v67, v67, 0, s[90:91]
	ds_write_b16 v181, v68 offset:576
	ds_write_b16 v181, v67 offset:848
	s_cbranch_vccnz .LBB0_1350
	v_add_u32_e32 v67, 0x1e000, v66
	ds_read_b32 v67, v67
	v_readlane_b32 s36, v254, 25
	v_readlane_b32 s37, v254, 26
	s_waitcnt lgkmcnt(0)
	v_sub_f32_e32 v68, v152, v67
	v_mul_f32_e32 v68, 0x3fb8aa3b, v68
	v_exp_f32_e32 v68, v68
	s_nop 0
	v_mul_f32_e32 v68, v6, v68
	v_cvt_pk_bf16_f32 v68, v68, s0
	v_cndmask_b32_e64 v68, v68, 0, s[36:37]
	ds_write_b16 v181, v68 offset:64
	v_sub_f32_e32 v68, v153, v67
	v_mul_f32_e32 v68, 0x3fb8aa3b, v68
	v_exp_f32_e32 v68, v68
	v_readlane_b32 s36, v254, 7
	v_readlane_b32 s37, v254, 8
	v_mul_f32_e32 v68, v7, v68
	v_cvt_pk_bf16_f32 v68, v68, s0
	v_cndmask_b32_e64 v68, v68, 0, s[36:37]
	ds_write_b16 v181, v68 offset:336
	v_sub_f32_e32 v68, v121, v67
	v_mul_f32_e32 v68, 0x3fb8aa3b, v68
	v_exp_f32_e32 v68, v68
	v_sub_f32_e32 v67, v119, v67
	v_mul_f32_e32 v67, 0x3fb8aa3b, v67
	v_exp_f32_e32 v67, v67
	v_mul_f32_e32 v68, v8, v68
	v_readlane_b32 s36, v255, 19
	v_cvt_pk_bf16_f32 v68, v68, s0
	v_readlane_b32 s37, v255, 20
	v_mul_f32_e32 v67, v9, v67
	v_cvt_pk_bf16_f32 v67, v67, s0
	v_cndmask_b32_e64 v68, v68, 0, s[36:37]
	v_readlane_b32 s36, v255, 21
	v_readlane_b32 s37, v255, 22
	ds_write_b16 v181, v68 offset:608
	s_nop 0
	v_cndmask_b32_e64 v67, v67, 0, s[36:37]
	ds_write_b16 v181, v67 offset:880
	s_andn2_b64 vcc, exec, s[94:95]
	s_cbranch_vccz .LBB0_1351

.LBB0_1358:
	s_waitcnt vmcnt(5)
	v_div_scale_f32 v86, s[70:71], v85, v85, 1.0
	v_rcp_f32_e32 v87, v86
	v_add_u32_e32 v148, s73, v125
	ds_read_b128 v[184:187], v148 offset:65280
	v_mul_f32_e32 v152, 0x3fb8aa3b, v152
	v_fma_f32 v88, -v86, v87, 1.0
	v_fmac_f32_e32 v87, v88, v87
	v_div_scale_f32 v88, vcc, 1.0, v85, 1.0
	v_mul_f32_e32 v89, v88, v87
	v_fma_f32 v90, -v86, v89, v88
	v_fmac_f32_e32 v89, v90, v87
	v_fma_f32 v86, -v86, v89, v88
	v_div_fmas_f32 v86, v86, v87, v89
	v_div_fixup_f32 v151, v86, v85, 1.0
	v_div_scale_f32 v85, s[70:71], v84, v84, 1.0
	v_rcp_f32_e32 v86, v85
	ds_read_b128 v[90:93], v148 offset:56576
	ds_read_b128 v[94:97], v148 offset:60928
	v_mul_f32_e32 v153, 0x3fb8aa3b, v153
	v_fma_f32 v87, -v85, v86, 1.0
	v_fmac_f32_e32 v86, v87, v86
	v_div_scale_f32 v87, vcc, 1.0, v84, 1.0
	v_mul_f32_e32 v88, v87, v86
	v_fma_f32 v89, -v85, v88, v87
	v_fmac_f32_e32 v88, v89, v86
	v_fma_f32 v85, -v85, v88, v87
	v_div_fmas_f32 v85, v85, v86, v88
	v_div_fixup_f32 v150, v85, v84, 1.0
	s_waitcnt vmcnt(3)
	v_div_scale_f32 v84, s[70:71], v83, v83, 1.0
	v_rcp_f32_e32 v85, v84
	v_exp_f32_e32 v152, v152
	v_exp_f32_e32 v153, v153
	v_readlane_b32 s36, v254, 63
	v_fma_f32 v86, -v84, v85, 1.0
	v_fmac_f32_e32 v85, v86, v85
	v_div_scale_f32 v86, vcc, 1.0, v83, 1.0
	v_mul_f32_e32 v87, v86, v85
	v_fma_f32 v88, -v84, v87, v86
	v_fmac_f32_e32 v87, v88, v85
	v_fma_f32 v84, -v84, v87, v86
	v_div_fmas_f32 v84, v84, v85, v87
	v_div_fixup_f32 v147, v84, v83, 1.0
	v_div_scale_f32 v83, s[70:71], v82, v82, 1.0
	v_rcp_f32_e32 v84, v83
	v_readlane_b32 s50, v255, 13
	v_readlane_b32 s51, v255, 14
	v_readlane_b32 s37, v255, 0
	v_fma_f32 v85, -v83, v84, 1.0
	v_fmac_f32_e32 v84, v85, v84
	v_div_scale_f32 v85, vcc, 1.0, v82, 1.0
	v_mul_f32_e32 v86, v85, v84
	v_fma_f32 v87, -v83, v86, v85
	v_fmac_f32_e32 v86, v87, v84
	v_fma_f32 v83, -v83, v86, v85
	v_div_fmas_f32 v83, v83, v84, v86
	v_div_fixup_f32 v146, v83, v82, 1.0
	ds_read_b128 v[82:85], v113
	ds_read_b128 v[86:89], v148 offset:52224
	s_waitcnt lgkmcnt(0)
	v_mfma_f32_16x16x32_bf16 v[86:89], v[82:85], v[86:89], 0
	v_readlane_b32 s38, v255, 1
	v_readlane_b32 s39, v255, 2
	v_readlane_b32 s40, v255, 3
	v_mfma_f32_16x16x32_bf16 v[90:93], v[82:85], v[90:93], 0
	v_readlane_b32 s41, v255, 4
	v_readlane_b32 s42, v255, 5
	v_readlane_b32 s43, v255, 6
	v_mfma_f32_16x16x32_bf16 v[94:97], v[82:85], v[94:97], 0
	v_readlane_b32 s44, v255, 7
	v_readlane_b32 s45, v255, 8
	v_readlane_b32 s46, v255, 9
	v_mfma_f32_16x16x32_bf16 v[82:85], v[82:85], v[184:187], 0
	ds_read_b128 v[184:187], v113 offset:64
	ds_read_b128 v[188:191], v148 offset:52288
	v_readlane_b32 s47, v255, 10
	v_readlane_b32 s48, v255, 11
	s_waitcnt lgkmcnt(0)
	v_mfma_f32_16x16x32_bf16 v[86:89], v[184:187], v[188:191], v[86:89]
	ds_read_b128 v[188:191], v148 offset:56640
	v_readlane_b32 s49, v255, 12
	s_waitcnt lgkmcnt(0)
	v_mfma_f32_16x16x32_bf16 v[90:93], v[184:187], v[188:191], v[90:93]
	ds_read_b128 v[188:191], v148 offset:60992
	s_waitcnt lgkmcnt(0)
	v_mfma_f32_16x16x32_bf16 v[94:97], v[184:187], v[188:191], v[94:97]
	ds_read_b128 v[188:191], v148 offset:65344
	s_waitcnt lgkmcnt(0)
	v_mfma_f32_16x16x32_bf16 v[82:85], v[184:187], v[188:191], v[82:85]
	ds_read_b128 v[184:187], v113 offset:128
	ds_read_b128 v[188:191], v148 offset:52352
	s_waitcnt lgkmcnt(0)
	v_mfma_f32_16x16x32_bf16 v[86:89], v[184:187], v[188:191], v[86:89]
	ds_read_b128 v[188:191], v148 offset:56704
	s_waitcnt lgkmcnt(0)
	v_mfma_f32_16x16x32_bf16 v[90:93], v[184:187], v[188:191], v[90:93]
	ds_read_b128 v[188:191], v148 offset:61056
	s_waitcnt lgkmcnt(0)
	v_mfma_f32_16x16x32_bf16 v[188:191], v[184:187], v[188:191], v[94:97]
	s_nop 2
	ds_read_b128 v[94:97], v148 offset:65408
	s_waitcnt lgkmcnt(0)
	v_mfma_f32_16x16x32_bf16 v[82:85], v[184:187], v[94:97], v[82:85]
	ds_read_b128 v[184:187], v113 offset:192
	ds_read_b128 v[94:97], v148 offset:52416
	s_waitcnt lgkmcnt(0)
	v_mfma_f32_16x16x32_bf16 v[94:97], v[184:187], v[94:97], v[86:89]
	s_nop 2
	ds_read_b128 v[86:89], v148 offset:56768
	s_waitcnt lgkmcnt(0)
	v_mfma_f32_16x16x32_bf16 v[90:93], v[184:187], v[86:89], v[90:93]
	ds_read_b128 v[86:89], v148 offset:61120
	s_nop 0
	v_pk_fma_f32 v[78:79], v[152:153], v[94:95], v[78:79]
	s_nop 4
	v_pk_fma_f32 v[90:91], v[152:153], v[90:91], v[74:75]
	s_waitcnt lgkmcnt(0)
	v_mfma_f32_16x16x32_bf16 v[86:89], v[184:187], v[86:89], v[188:191]
	s_nop 2
	ds_read_b128 v[188:191], v148 offset:65472
	s_waitcnt lgkmcnt(0)
	v_mfma_f32_16x16x32_bf16 v[82:85], v[184:187], v[188:191], v[82:85]
	ds_read_u16 v183, v117 offset:17408
	ds_read_u16 v187, v117 offset:17440
	ds_read_u16 v184, v178
	ds_read_u16 v185, v178 offset:32
	ds_read_u16 v190, v117 offset:17472
	ds_read_u16 v191, v178 offset:64
	ds_read_u16 v192, v117 offset:17504
	ds_read_u16 v186, v178 offset:96
	ds_read_u16 v188, v117 offset:17680
	ds_read_u16 v189, v178 offset:128
	ds_read_u16 v193, v117 offset:17712
	ds_read_u16 v194, v178 offset:160
	ds_read_u16 v195, v117 offset:17744
	ds_read_u16 v196, v178 offset:192
	ds_read_u16 v197, v117 offset:17776
	ds_read_u16 v198, v178 offset:224
	s_waitcnt lgkmcnt(13)
	v_lshlrev_b32_e32 v200, 16, v184
	s_waitcnt lgkmcnt(12)
	v_lshlrev_b32_e32 v201, 16, v185
	v_mul_f32_e32 v184, 0xbfb8aa3b, v200
	v_mul_f32_e32 v185, 0xbfb8aa3b, v201
	s_waitcnt lgkmcnt(8)
	v_lshlrev_b32_e32 v199, 16, v186
	v_exp_f32_e32 v184, v184
	v_exp_f32_e32 v186, v185
	s_waitcnt lgkmcnt(4)
	v_lshlrev_b32_e32 v194, 16, v194
	v_mul_f32_e32 v74, 0xbfb8aa3b, v194
	v_pk_fma_f32 v[70:71], v[152:153], v[86:87], v[70:71]
	s_waitcnt lgkmcnt(0)
	v_lshlrev_b32_e32 v198, 16, v198
	v_pk_fma_f32 v[66:67], v[152:153], v[82:83], v[66:67]
	v_mul_f32_e32 v82, 0xbfb8aa3b, v198
	s_waitcnt vmcnt(2)
	v_mov_b32_e32 v148, v238
	v_pk_mul_f32 v[154:155], v[150:151], v[148:149] op_sel_hi:[1,0]
	v_lshlrev_b32_e32 v151, 16, v189
	v_mul_f32_e32 v94, 0xbfb8aa3b, v151
	v_exp_f32_e32 v185, v94
	v_lshlrev_b32_e32 v189, 16, v188
	v_lshlrev_b32_e32 v188, 16, v183
	v_mul_f32_e32 v150, 0xbfb8aa3b, v199
	v_pk_add_f32 v[94:95], v[184:185], 1.0 op_sel_hi:[1,0]
	v_exp_f32_e32 v150, v150
	v_div_scale_f32 v183, s[70:71], v95, v95, v151
	v_rcp_f32_e32 v184, v183
	s_nop 0
	v_fma_f32 v185, -v183, v184, 1.0
	v_fmac_f32_e32 v184, v185, v184
	v_div_scale_f32 v185, vcc, v151, v95, v151
	v_mul_f32_e32 v202, v185, v184
	v_fma_f32 v203, -v183, v202, v185
	v_fmac_f32_e32 v202, v203, v184
	v_fma_f32 v183, -v183, v202, v185
	v_div_fmas_f32 v183, v183, v184, v202
	v_div_fixup_f32 v95, v183, v95, v151
	v_div_scale_f32 v151, s[70:71], v94, v94, v200
	v_rcp_f32_e32 v183, v151
	s_nop 0
	v_fma_f32 v184, -v151, v183, 1.0
	v_fmac_f32_e32 v183, v184, v183
	v_div_scale_f32 v184, vcc, v200, v94, v200
	v_mul_f32_e32 v185, v184, v183
	v_fma_f32 v202, -v151, v185, v184
	v_fmac_f32_e32 v185, v202, v183
	v_fma_f32 v151, -v151, v185, v184
	v_lshlrev_b32_e32 v184, 16, v187
	v_exp_f32_e32 v187, v74
	v_div_fmas_f32 v151, v151, v183, v185
	v_div_fixup_f32 v94, v151, v94, v200
	v_lshlrev_b32_e32 v185, 16, v193
	v_pk_add_f32 v[74:75], v[186:187], 1.0 op_sel_hi:[1,0]
	s_nop 0
	v_div_scale_f32 v151, s[70:71], v75, v75, v194
	v_rcp_f32_e32 v183, v151
	s_nop 0
	v_fma_f32 v186, -v151, v183, 1.0
	v_fmac_f32_e32 v183, v186, v183
	v_div_scale_f32 v186, vcc, v194, v75, v194
	v_mul_f32_e32 v187, v186, v183
	v_fma_f32 v193, -v151, v187, v186
	v_fmac_f32_e32 v187, v193, v183
	v_fma_f32 v151, -v151, v187, v186
	v_div_fmas_f32 v151, v151, v183, v187
	v_div_fixup_f32 v187, v151, v75, v194
	v_div_scale_f32 v75, s[70:71], v74, v74, v201
	v_rcp_f32_e32 v151, v75
	s_nop 0
	v_fma_f32 v183, -v75, v151, 1.0
	v_fmac_f32_e32 v151, v183, v151
	v_div_scale_f32 v183, vcc, v201, v74, v201
	v_mul_f32_e32 v186, v183, v151
	v_fma_f32 v193, -v75, v186, v183
	v_fmac_f32_e32 v186, v193, v151
	v_fma_f32 v75, -v75, v186, v183
	v_div_fmas_f32 v75, v75, v151, v186
	v_lshlrev_b32_e32 v151, 16, v196
	v_lshlrev_b32_e32 v183, 16, v191
	v_div_fixup_f32 v186, v75, v74, v201
	v_pk_fma_f32 v[74:75], v[154:155], v[188:189], v[78:79]
	v_pk_fma_f32 v[78:79], v[154:155], v[184:185], v[90:91]
	v_mul_f32_e32 v90, 0xbfb8aa3b, v183
	v_mul_f32_e32 v86, 0xbfb8aa3b, v151
	v_exp_f32_e32 v90, v90
	v_exp_f32_e32 v91, v86
	v_pk_mul_f32 v[78:79], v[78:79], v[186:187]
	v_pk_mul_f32 v[74:75], v[74:75], v[94:95]
	v_lshlrev_b32_e32 v95, 16, v195
	v_pk_add_f32 v[86:87], v[90:91], 1.0 op_sel_hi:[1,0]
	v_lshlrev_b32_e32 v94, 16, v190
	v_div_scale_f32 v90, s[70:71], v87, v87, v151
	v_rcp_f32_e32 v91, v90
	v_pk_fma_f32 v[70:71], v[154:155], v[94:95], v[70:71]
	v_fma_f32 v184, -v90, v91, 1.0
	v_fmac_f32_e32 v91, v184, v91
	v_div_scale_f32 v184, vcc, v151, v87, v151
	v_mul_f32_e32 v185, v184, v91
	v_fma_f32 v186, -v90, v185, v184
	v_fmac_f32_e32 v185, v186, v91
	v_fma_f32 v90, -v90, v185, v184
	v_div_fmas_f32 v90, v90, v91, v185
	v_div_fixup_f32 v87, v90, v87, v151
	v_div_scale_f32 v90, s[70:71], v86, v86, v183
	v_rcp_f32_e32 v91, v90
	s_nop 0
	v_fma_f32 v151, -v90, v91, 1.0
	v_fmac_f32_e32 v91, v151, v91
	v_div_scale_f32 v151, vcc, v183, v86, v183
	v_mul_f32_e32 v184, v151, v91
	v_fma_f32 v185, -v90, v184, v151
	v_fmac_f32_e32 v184, v185, v91
	v_fma_f32 v90, -v90, v184, v151
	v_exp_f32_e32 v151, v82
	v_div_fmas_f32 v90, v90, v91, v184
	v_div_fixup_f32 v86, v90, v86, v183
	v_pk_mul_f32 v[70:71], v[70:71], v[86:87]
	v_lshlrev_b32_e32 v87, 16, v197
	v_lshlrev_b32_e32 v86, 16, v192
	v_pk_add_f32 v[82:83], v[150:151], 1.0 op_sel_hi:[1,0]
	v_pk_fma_f32 v[66:67], v[154:155], v[86:87], v[66:67]
	v_div_scale_f32 v86, s[70:71], v83, v83, v198
	v_rcp_f32_e32 v87, v86
	s_nop 0
	v_fma_f32 v90, -v86, v87, 1.0
	v_fmac_f32_e32 v87, v90, v87
	v_div_scale_f32 v90, vcc, v198, v83, v198
	v_mul_f32_e32 v91, v90, v87
	v_fma_f32 v94, -v86, v91, v90
	v_fmac_f32_e32 v91, v94, v87
	v_fma_f32 v86, -v86, v91, v90
	v_div_fmas_f32 v86, v86, v87, v91
	v_div_fixup_f32 v83, v86, v83, v198
	v_div_scale_f32 v86, s[70:71], v82, v82, v199
	v_rcp_f32_e32 v87, v86
	s_nop 0
	v_fma_f32 v90, -v86, v87, 1.0
	v_fmac_f32_e32 v87, v90, v87
	v_div_scale_f32 v90, vcc, v199, v82, v199
	v_mul_f32_e32 v91, v90, v87
	v_fma_f32 v94, -v86, v91, v90
	v_fmac_f32_e32 v91, v94, v87
	v_fma_f32 v86, -v86, v91, v90
	v_div_fmas_f32 v86, v86, v87, v91
	v_div_fixup_f32 v82, v86, v82, v199
	v_pk_mul_f32 v[66:67], v[66:67], v[82:83]
	v_mul_f32_e32 v82, 0x3fb8aa3b, v121
	ds_read_u16 v87, v117 offset:17952
	ds_read_u16 v94, v178 offset:256
	ds_read_u16 v121, v117 offset:17984
	ds_read_u16 v95, v178 offset:288
	ds_read_u16 v152, v117 offset:18016
	ds_read_u16 v153, v178 offset:320
	ds_read_u16 v154, v117 offset:18048
	ds_read_u16 v86, v178 offset:352
	v_mul_f32_e32 v83, 0x3fb8aa3b, v119
	ds_read_u16 v119, v117 offset:18224
	ds_read_u16 v150, v178 offset:384
	ds_read_u16 v155, v117 offset:18256
	ds_read_u16 v151, v178 offset:416
	ds_read_u16 v183, v117 offset:18288
	ds_read_u16 v184, v178 offset:448
	ds_read_u16 v185, v117 offset:18320
	ds_read_u16 v186, v178 offset:480
	v_pk_mul_f32 v[90:91], v[146:147], v[148:149] op_sel_hi:[1,0]
	s_waitcnt lgkmcnt(6)
	v_lshlrev_b32_e32 v147, 16, v150
	v_lshlrev_b32_e32 v187, 16, v94
	v_lshlrev_b32_e32 v189, 16, v95
	v_mul_f32_e32 v94, 0xbfb8aa3b, v187
	v_mul_f32_e32 v95, 0xbfb8aa3b, v189
	v_lshlrev_b32_e32 v150, 16, v87
	v_mul_f32_e32 v87, 0xbfb8aa3b, v147
	v_exp_f32_e32 v94, v94
	v_exp_f32_e32 v146, v95
	v_exp_f32_e32 v95, v87
	v_exp_f32_e32 v82, v82
	v_exp_f32_e32 v83, v83
	s_waitcnt lgkmcnt(4)
	v_lshlrev_b32_e32 v188, 16, v151
	v_pk_add_f32 v[94:95], v[94:95], 1.0 op_sel_hi:[1,0]
	v_lshlrev_b32_e32 v151, 16, v119
	v_div_scale_f32 v87, s[70:71], v95, v95, v147
	v_pk_fma_f32 v[80:81], v[82:83], v[96:97], v[80:81]
	v_rcp_f32_e32 v96, v87
	v_pk_fma_f32 v[92:93], v[82:83], v[92:93], v[76:77]
	v_mul_f32_e32 v76, 0xbfb8aa3b, v188
	v_pk_fma_f32 v[72:73], v[82:83], v[88:89], v[72:73]
	v_fma_f32 v97, -v87, v96, 1.0
	v_fmac_f32_e32 v96, v97, v96
	v_div_scale_f32 v97, vcc, v147, v95, v147
	v_mul_f32_e32 v119, v97, v96
	v_fma_f32 v190, -v87, v119, v97
	v_fmac_f32_e32 v119, v190, v96
	v_fma_f32 v87, -v87, v119, v97
	v_div_fmas_f32 v87, v87, v96, v119
	v_div_fixup_f32 v95, v87, v95, v147
	v_div_scale_f32 v87, s[70:71], v94, v94, v187
	v_rcp_f32_e32 v96, v87
	s_waitcnt lgkmcnt(0)
	v_lshlrev_b32_e32 v148, 16, v186
	v_lshlrev_b32_e32 v186, 16, v86
	v_mul_f32_e32 v86, 0xbfb8aa3b, v186
	v_fma_f32 v97, -v87, v96, 1.0
	v_fmac_f32_e32 v96, v97, v96
	v_div_scale_f32 v97, vcc, v187, v94, v187
	v_mul_f32_e32 v119, v97, v96
	v_fma_f32 v147, -v87, v119, v97
	v_fmac_f32_e32 v119, v147, v96
	v_exp_f32_e32 v147, v76
	v_fma_f32 v87, -v87, v119, v97
	v_div_fmas_f32 v87, v87, v96, v119
	v_div_fixup_f32 v94, v87, v94, v187
	v_pk_add_f32 v[76:77], v[146:147], 1.0 op_sel_hi:[1,0]
	v_lshlrev_b32_e32 v96, 16, v121
	v_div_scale_f32 v87, s[70:71], v77, v77, v188
	v_rcp_f32_e32 v119, v87
	v_lshlrev_b32_e32 v97, 16, v155
	v_pk_fma_f32 v[68:69], v[82:83], v[84:85], v[68:69]
	v_mul_f32_e32 v82, 0xbfb8aa3b, v148
	v_fma_f32 v121, -v87, v119, 1.0
	v_fmac_f32_e32 v119, v121, v119
	v_div_scale_f32 v121, vcc, v188, v77, v188
	v_mul_f32_e32 v146, v121, v119
	v_fma_f32 v147, -v87, v146, v121
	v_fmac_f32_e32 v146, v147, v119
	v_fma_f32 v87, -v87, v146, v121
	v_div_fmas_f32 v87, v87, v119, v146
	v_div_fixup_f32 v147, v87, v77, v188
	v_div_scale_f32 v77, s[70:71], v76, v76, v189
	v_rcp_f32_e32 v87, v77
	v_exp_f32_e32 v86, v86
	s_waitcnt lgkmcnt(0)
	v_fma_f32 v119, -v77, v87, 1.0
	v_fmac_f32_e32 v87, v119, v87
	v_div_scale_f32 v119, vcc, v189, v76, v189
	v_mul_f32_e32 v121, v119, v87
	v_fma_f32 v146, -v77, v121, v119
	v_fmac_f32_e32 v121, v146, v87
	v_fma_f32 v77, -v77, v121, v119
	v_div_fmas_f32 v77, v77, v87, v121
	v_div_fixup_f32 v146, v77, v76, v189
	v_pk_fma_f32 v[76:77], v[90:91], v[150:151], v[80:81]
	v_pk_fma_f32 v[80:81], v[90:91], v[96:97], v[92:93]
	v_lshlrev_b32_e32 v87, 16, v184
	v_lshlrev_b32_e32 v96, 16, v153
	v_mul_f32_e32 v92, 0xbfb8aa3b, v96
	v_mul_f32_e32 v88, 0xbfb8aa3b, v87
	v_exp_f32_e32 v92, v92
	v_exp_f32_e32 v93, v88
	v_pk_mul_f32 v[76:77], v[76:77], v[94:95]
	v_lshlrev_b32_e32 v95, 16, v183
	v_lshlrev_b32_e32 v94, 16, v152
	v_pk_add_f32 v[88:89], v[92:93], 1.0 op_sel_hi:[1,0]
	v_pk_fma_f32 v[72:73], v[90:91], v[94:95], v[72:73]
	v_div_scale_f32 v92, s[70:71], v89, v89, v87
	v_rcp_f32_e32 v93, v92
	v_pk_mul_f32 v[80:81], v[80:81], v[146:147]
	v_fma_f32 v97, -v92, v93, 1.0
	v_fmac_f32_e32 v93, v97, v93
	v_div_scale_f32 v97, vcc, v87, v89, v87
	v_mul_f32_e32 v119, v97, v93
	v_fma_f32 v121, -v92, v119, v97
	v_fmac_f32_e32 v119, v121, v93
	v_fma_f32 v92, -v92, v119, v97
	v_div_fmas_f32 v92, v92, v93, v119
	v_div_fixup_f32 v89, v92, v89, v87
	v_div_scale_f32 v87, s[70:71], v88, v88, v96
	v_rcp_f32_e32 v92, v87
	s_nop 0
	v_fma_f32 v93, -v87, v92, 1.0
	v_fmac_f32_e32 v92, v93, v92
	v_div_scale_f32 v93, vcc, v96, v88, v96
	v_mul_f32_e32 v97, v93, v92
	v_fma_f32 v119, -v87, v97, v93
	v_fmac_f32_e32 v97, v119, v92
	v_fma_f32 v87, -v87, v97, v93
	v_div_fmas_f32 v87, v87, v92, v97
	v_div_fixup_f32 v88, v87, v88, v96
	v_exp_f32_e32 v87, v82
	v_pk_mul_f32 v[72:73], v[72:73], v[88:89]
	v_lshlrev_b32_e32 v89, 16, v185
	v_lshlrev_b32_e32 v88, 16, v154
	v_pk_add_f32 v[82:83], v[86:87], 1.0 op_sel_hi:[1,0]
	v_pk_fma_f32 v[68:69], v[90:91], v[88:89], v[68:69]
	v_div_scale_f32 v84, s[70:71], v83, v83, v148
	v_rcp_f32_e32 v85, v84
	v_lshl_add_u64 v[90:91], s[50:51], 0, v[142:143]
	v_fma_f32 v86, -v84, v85, 1.0
	v_fmac_f32_e32 v85, v86, v85
	v_div_scale_f32 v86, vcc, v148, v83, v148
	v_mul_f32_e32 v87, v86, v85
	v_fma_f32 v88, -v84, v87, v86
	v_fmac_f32_e32 v87, v88, v85
	v_fma_f32 v84, -v84, v87, v86
	v_div_fmas_f32 v84, v84, v85, v87
	v_div_fixup_f32 v83, v84, v83, v148
	v_div_scale_f32 v84, s[70:71], v82, v82, v186
	v_rcp_f32_e32 v85, v84
	s_nop 0
	v_fma_f32 v86, -v84, v85, 1.0
	v_fmac_f32_e32 v85, v86, v85
	v_div_scale_f32 v86, vcc, v186, v82, v186
	v_mul_f32_e32 v87, v86, v85
	v_fma_f32 v88, -v84, v87, v86
	v_fmac_f32_e32 v87, v88, v85
	v_fma_f32 v84, -v84, v87, v86
	v_div_fmas_f32 v84, v84, v85, v87
	v_div_fixup_f32 v82, v84, v82, v186
	v_pk_mul_f32 v[68:69], v[68:69], v[82:83]
	v_cvt_pk_bf16_f32 v82, v74, s0
	ds_write_b16 v178, v82
	v_cvt_pk_bf16_f32 v82, v78, s0
	ds_write_b16 v178, v82 offset:32
	v_cvt_pk_bf16_f32 v82, v70, s0
	ds_write_b16 v178, v82 offset:64
	v_cvt_pk_bf16_f32 v82, v66, s0
	ds_write_b16 v178, v82 offset:96
	v_cvt_pk_bf16_f32 v82, v75, s0
	ds_write_b16 v178, v82 offset:128
	v_cvt_pk_bf16_f32 v82, v79, s0
	ds_write_b16 v178, v82 offset:160
	v_cvt_pk_bf16_f32 v82, v71, s0
	ds_write_b16 v178, v82 offset:192
	v_cvt_pk_bf16_f32 v82, v67, s0
	ds_write_b16 v178, v82 offset:224
	v_cvt_pk_bf16_f32 v82, v76, s0
	ds_write_b16 v178, v82 offset:256
	v_cvt_pk_bf16_f32 v82, v80, s0
	ds_write_b16 v178, v82 offset:288
	v_cvt_pk_bf16_f32 v82, v72, s0
	ds_write_b16 v178, v82 offset:320
	v_cvt_pk_bf16_f32 v82, v68, s0
	ds_write_b16 v178, v82 offset:352
	v_cvt_pk_bf16_f32 v82, v77, s0
	ds_write_b16 v178, v82 offset:384
	v_cvt_pk_bf16_f32 v82, v81, s0
	ds_write_b16 v178, v82 offset:416
	v_cvt_pk_bf16_f32 v82, v73, s0
	ds_write_b16 v178, v82 offset:448
	v_cvt_pk_bf16_f32 v82, v69, s0
	ds_write_b16 v178, v82 offset:480
	s_waitcnt lgkmcnt(0)
	ds_read_b128 v[82:85], v180
	ds_read_b128 v[86:89], v180 offset:1024
	v_add_co_u32_e32 v92, vcc, 0x10000000, v90
	s_nop 1
	v_addc_co_u32_e32 v93, vcc, 0, v91, vcc
	s_waitcnt lgkmcnt(1)
	global_store_dwordx4 v[92:93], v[82:85], off offset:2048
	s_nop 1
	v_add_co_u32_e32 v82, vcc, 0x10008000, v90
	s_nop 1
	v_addc_co_u32_e32 v83, vcc, 0, v91, vcc
	s_andn2_b64 vcc, exec, s[66:67]
	s_waitcnt lgkmcnt(0)
	global_store_dwordx4 v[82:83], v[86:89], off offset:2048
	s_barrier
	s_waitcnt vmcnt(2)
	ds_write_b128 v180, v[226:229]
	ds_write_b128 v180, v[230:233] offset:1024
	s_cbranch_vccnz .LBB0_1336
	v_lshlrev_b32_e32 v82, 16, v38
	v_and_b32_e32 v83, 0xffff0000, v38
	v_lshlrev_b32_e32 v84, 16, v39
	v_and_b32_e32 v85, 0xffff0000, v39
	v_pk_mul_f32 v[82:83], v[122:123], v[82:83] op_sel_hi:[0,1]
	v_pk_mul_f32 v[84:85], v[122:123], v[84:85] op_sel_hi:[0,1]
	v_cvt_pk_bf16_f32 v82, v82, v83
	v_cvt_pk_bf16_f32 v83, v84, v85
	v_lshlrev_b32_e32 v84, 16, v40
	v_and_b32_e32 v85, 0xffff0000, v40
	v_lshlrev_b32_e32 v86, 16, v41
	v_and_b32_e32 v87, 0xffff0000, v41
	v_pk_mul_f32 v[84:85], v[122:123], v[84:85] op_sel_hi:[0,1]
	v_pk_mul_f32 v[86:87], v[122:123], v[86:87] op_sel_hi:[0,1]
	v_cvt_pk_bf16_f32 v84, v84, v85
	v_cvt_pk_bf16_f32 v85, v86, v87
	ds_write_b128 v127, v[82:85] offset:17408
	ds_write_b128 v127, v[42:45] offset:52224
	s_and_saveexec_b64 s[66:67], s[10:11]
	s_cbranch_execz .LBB0_1364
	v_lshlrev_b32_e32 v82, 16, v34
	v_and_b32_e32 v83, 0xffff0000, v34
	v_lshlrev_b32_e32 v84, 16, v35
	v_and_b32_e32 v85, 0xffff0000, v35
	v_pk_mul_f32 v[82:83], v[124:125], v[82:83] op_sel_hi:[0,1]
	v_pk_mul_f32 v[84:85], v[124:125], v[84:85] op_sel_hi:[0,1]
	v_cvt_pk_bf16_f32 v82, v82, v83
	v_cvt_pk_bf16_f32 v83, v84, v85
	v_lshlrev_b32_e32 v84, 16, v36
	v_and_b32_e32 v85, 0xffff0000, v36
	v_lshlrev_b32_e32 v86, 16, v37
	v_and_b32_e32 v87, 0xffff0000, v37
	v_pk_mul_f32 v[84:85], v[124:125], v[84:85] op_sel_hi:[0,1]
	v_pk_mul_f32 v[86:87], v[124:125], v[86:87] op_sel_hi:[0,1]
	v_cvt_pk_bf16_f32 v84, v84, v85
	v_cvt_pk_bf16_f32 v85, v86, v87
	ds_write_b128 v127, v[82:85] offset:26112
	s_or_b64 exec, exec, s[66:67]
	ds_write_b128 v127, v[54:57] offset:60928
	s_and_saveexec_b64 s[66:67], s[12:13]
	s_cbranch_execnz .LBB0_1365
